# S5 tile loop: the 4th B-multiply MFMA issued after the first four lane swaps (swaps of the first MFMA pair run under MFMA 3/4 instead of after all four MFMAs)
# speedup vs baseline: 1.0085x; 1.0085x over previous
.Ls5p_tile:
	v_mfma_f32_32x32x16_bf16 v[0:15], v[68:71], v[32:35], 0
	v_mfma_f32_32x32x16_bf16 v[112:127], v[68:71], v[40:43], 0
	v_mfma_f32_32x32x16_bf16 v[16:31], v[68:71], v[36:39], 0
	s_cmp_lt_u32 s6, 63
	s_cbranch_scc1 .Ls5p_ld
	s_nop 7
	s_branch .Ls5p_swap
.Ls5p_ld:
	global_load_dwordx2 v[190:191], v[232:233], off
	global_load_dwordx2 v[192:193], v[234:235], off
	v_lshl_add_u64 v[232:233], v[232:233], 0, s[50:51]
	v_lshl_add_u64 v[234:235], v[234:235], 0, s[50:51]
	s_nop 3
.Ls5p_swap:
	v_permlane32_swap_b32_e32 v0, v112
	v_permlane32_swap_b32_e32 v1, v113
	v_permlane32_swap_b32_e32 v2, v114
	v_permlane32_swap_b32_e32 v3, v115
	v_mfma_f32_32x32x16_bf16 v[160:175], v[68:71], v[44:47], 0
	s_cbranch_scc0 .Ls5p_nold
	global_load_dwordx4 v[68:71], v[230:231], off
	v_lshl_add_u64 v[230:231], v[230:231], 0, s[50:51]
.Ls5p_nold:
	v_permlane32_swap_b32_e32 v4, v116
	v_permlane32_swap_b32_e32 v5, v117
	v_permlane32_swap_b32_e32 v6, v118
	v_permlane32_swap_b32_e32 v7, v119
	v_permlane32_swap_b32_e32 v8, v120
	v_permlane32_swap_b32_e32 v9, v121
	v_permlane32_swap_b32_e32 v10, v122
	v_permlane32_swap_b32_e32 v11, v123
	v_permlane32_swap_b32_e32 v12, v124
	v_permlane32_swap_b32_e32 v13, v125
	v_permlane32_swap_b32_e32 v14, v126
	v_permlane32_swap_b32_e32 v15, v127
	v_permlane32_swap_b32_e32 v16, v160
	v_permlane32_swap_b32_e32 v17, v161
	v_permlane32_swap_b32_e32 v18, v162
	v_permlane32_swap_b32_e32 v19, v163
	v_permlane32_swap_b32_e32 v20, v164
	v_permlane32_swap_b32_e32 v21, v165
	v_permlane32_swap_b32_e32 v22, v166
	v_permlane32_swap_b32_e32 v23, v167
	v_permlane32_swap_b32_e32 v24, v168
	v_permlane32_swap_b32_e32 v25, v169
	v_permlane32_swap_b32_e32 v26, v170
	v_permlane32_swap_b32_e32 v27, v171
	v_permlane32_swap_b32_e32 v28, v172
	v_permlane32_swap_b32_e32 v29, v173
	v_permlane32_swap_b32_e32 v30, v174
	v_permlane32_swap_b32_e32 v31, v175
	v_fmac_f32_e32 v0, v80, v103
	v_fmac_f32_e32 v16, v80, v102
	v_fmac_f32_e32 v0, v89, v102
	v_fmac_f32_e32 v16, v81, v103
	v_fmac_f32_e32 v1, v80, v0
	v_fmac_f32_e32 v17, v80, v16
	v_cvt_pk_bf16_f32 v134, v0, v16
	v_fmac_f32_e32 v1, v89, v16
	v_fmac_f32_e32 v17, v81, v0
	v_fmac_f32_e32 v2, v80, v1
	v_fmac_f32_e32 v18, v80, v17
	v_cvt_pk_bf16_f32 v135, v1, v17
	v_fmac_f32_e32 v2, v89, v17
	v_fmac_f32_e32 v18, v81, v1
	ds_write_b32 v107, v134
	v_fmac_f32_e32 v3, v80, v2
	v_fmac_f32_e32 v19, v80, v18
	v_cvt_pk_bf16_f32 v136, v2, v18
	v_fmac_f32_e32 v3, v89, v18
	v_fmac_f32_e32 v19, v81, v2
	ds_write_b32 v107, v135 offset:528
	v_fmac_f32_e32 v112, v80, v3
	v_fmac_f32_e32 v160, v80, v19
	v_cvt_pk_bf16_f32 v137, v3, v19
	v_fmac_f32_e32 v112, v89, v19
	v_fmac_f32_e32 v160, v81, v3
	ds_write_b32 v107, v136 offset:1056
	v_fmac_f32_e32 v113, v80, v112
	v_fmac_f32_e32 v161, v80, v160
	v_cvt_pk_bf16_f32 v138, v112, v160
	v_fmac_f32_e32 v113, v89, v160
	v_fmac_f32_e32 v161, v81, v112
	ds_write_b32 v107, v137 offset:1584
	v_fmac_f32_e32 v114, v80, v113
	v_fmac_f32_e32 v162, v80, v161
	v_cvt_pk_bf16_f32 v139, v113, v161
	v_fmac_f32_e32 v114, v89, v161
	v_fmac_f32_e32 v162, v81, v113
	ds_write_b32 v107, v138 offset:2112
	v_fmac_f32_e32 v115, v80, v114
	v_fmac_f32_e32 v163, v80, v162
	v_cvt_pk_bf16_f32 v134, v114, v162
	v_fmac_f32_e32 v115, v89, v162
	v_fmac_f32_e32 v163, v81, v114
	ds_write_b32 v107, v139 offset:2640
	v_fmac_f32_e32 v4, v80, v115
	v_fmac_f32_e32 v20, v80, v163
	v_cvt_pk_bf16_f32 v135, v115, v163
	v_fmac_f32_e32 v4, v89, v163
	v_fmac_f32_e32 v20, v81, v115
	ds_write_b32 v107, v134 offset:3168
	v_fmac_f32_e32 v5, v80, v4
	v_fmac_f32_e32 v21, v80, v20
	v_cvt_pk_bf16_f32 v136, v4, v20
	v_fmac_f32_e32 v5, v89, v20
	v_fmac_f32_e32 v21, v81, v4
	ds_write_b32 v107, v135 offset:3696
	v_fmac_f32_e32 v6, v80, v5
	v_fmac_f32_e32 v22, v80, v21
	v_cvt_pk_bf16_f32 v137, v5, v21
	v_fmac_f32_e32 v6, v89, v21
	v_fmac_f32_e32 v22, v81, v5
	ds_write_b32 v107, v136 offset:4224
	v_fmac_f32_e32 v7, v80, v6
	v_fmac_f32_e32 v23, v80, v22
	v_cvt_pk_bf16_f32 v138, v6, v22
	v_fmac_f32_e32 v7, v89, v22
	v_fmac_f32_e32 v23, v81, v6
	ds_write_b32 v107, v137 offset:4752
	v_fmac_f32_e32 v116, v80, v7
	v_fmac_f32_e32 v164, v80, v23
	v_cvt_pk_bf16_f32 v139, v7, v23
	v_fmac_f32_e32 v116, v89, v23
	v_fmac_f32_e32 v164, v81, v7
	ds_write_b32 v107, v138 offset:5280
	v_fmac_f32_e32 v117, v80, v116
	v_fmac_f32_e32 v165, v80, v164
	v_cvt_pk_bf16_f32 v134, v116, v164
	v_fmac_f32_e32 v117, v89, v164
	v_fmac_f32_e32 v165, v81, v116
	ds_write_b32 v107, v139 offset:5808
	v_fmac_f32_e32 v118, v80, v117
	v_fmac_f32_e32 v166, v80, v165
	v_cvt_pk_bf16_f32 v135, v117, v165
	v_fmac_f32_e32 v118, v89, v165
	v_fmac_f32_e32 v166, v81, v117
	ds_write_b32 v107, v134 offset:6336
	v_fmac_f32_e32 v119, v80, v118
	v_fmac_f32_e32 v167, v80, v166
	v_cvt_pk_bf16_f32 v136, v118, v166
	v_fmac_f32_e32 v119, v89, v166
	v_fmac_f32_e32 v167, v81, v118
	ds_write_b32 v107, v135 offset:6864
	v_fmac_f32_e32 v8, v80, v119
	v_fmac_f32_e32 v24, v80, v167
	v_cvt_pk_bf16_f32 v137, v119, v167
	v_fmac_f32_e32 v8, v89, v167
	v_fmac_f32_e32 v24, v81, v119
	ds_write_b32 v107, v136 offset:7392
	v_fmac_f32_e32 v9, v80, v8
	v_fmac_f32_e32 v25, v80, v24
	v_cvt_pk_bf16_f32 v138, v8, v24
	v_fmac_f32_e32 v9, v89, v24
	v_fmac_f32_e32 v25, v81, v8
	ds_write_b32 v107, v137 offset:7920
	ds_read_b128 v[194:197], v108
	ds_read_b128 v[198:201], v108 offset:64
	ds_read_b128 v[202:205], v108 offset:128
	ds_read_b128 v[206:209], v108 offset:192
	v_fmac_f32_e32 v10, v80, v9
	v_fmac_f32_e32 v26, v80, v25
	v_cvt_pk_bf16_f32 v139, v9, v25
	v_fmac_f32_e32 v10, v89, v25
	v_fmac_f32_e32 v26, v81, v9
	ds_write_b32 v107, v138 offset:8448
	v_fmac_f32_e32 v11, v80, v10
	v_fmac_f32_e32 v27, v80, v26
	v_cvt_pk_bf16_f32 v134, v10, v26
	v_fmac_f32_e32 v11, v89, v26
	v_fmac_f32_e32 v27, v81, v10
	ds_write_b32 v107, v139 offset:8976
	v_fmac_f32_e32 v120, v80, v11
	v_fmac_f32_e32 v168, v80, v27
	v_cvt_pk_bf16_f32 v135, v11, v27
	v_fmac_f32_e32 v120, v89, v27
	v_fmac_f32_e32 v168, v81, v11
	ds_write_b32 v107, v134 offset:9504
	v_fmac_f32_e32 v121, v80, v120
	v_fmac_f32_e32 v169, v80, v168
	v_cvt_pk_bf16_f32 v136, v120, v168
	v_fmac_f32_e32 v121, v89, v168
	v_fmac_f32_e32 v169, v81, v120
	ds_write_b32 v107, v135 offset:10032
	v_fmac_f32_e32 v122, v80, v121
	v_fmac_f32_e32 v170, v80, v169
	v_cvt_pk_bf16_f32 v137, v121, v169
	v_fmac_f32_e32 v122, v89, v169
	v_fmac_f32_e32 v170, v81, v121
	ds_write_b32 v107, v136 offset:10560
	s_waitcnt lgkmcnt(5)
	v_mfma_f32_16x16x32_bf16 v[226:229], v[48:51], v[194:197], 0
	v_fmac_f32_e32 v123, v80, v122
	v_fmac_f32_e32 v171, v80, v170
	v_cvt_pk_bf16_f32 v138, v122, v170
	v_fmac_f32_e32 v123, v89, v170
	v_fmac_f32_e32 v171, v81, v122
	ds_write_b32 v107, v137 offset:11088
	v_mfma_f32_16x16x32_bf16 v[226:229], v[52:55], v[198:201], v[226:229]
	v_fmac_f32_e32 v12, v80, v123
	v_fmac_f32_e32 v28, v80, v171
	v_cvt_pk_bf16_f32 v139, v123, v171
	v_fmac_f32_e32 v12, v89, v171
	v_fmac_f32_e32 v28, v81, v123
	ds_write_b32 v107, v138 offset:11616
	v_mfma_f32_16x16x32_bf16 v[226:229], v[56:59], v[202:205], v[226:229]
	v_fmac_f32_e32 v13, v80, v12
	v_fmac_f32_e32 v29, v80, v28
	v_cvt_pk_bf16_f32 v134, v12, v28
	v_fmac_f32_e32 v13, v89, v28
	v_fmac_f32_e32 v29, v81, v12
	ds_write_b32 v107, v139 offset:12144
	v_mfma_f32_16x16x32_bf16 v[226:229], v[60:63], v[206:209], v[226:229]
	v_fmac_f32_e32 v14, v80, v13
	v_fmac_f32_e32 v30, v80, v29
	v_cvt_pk_bf16_f32 v135, v13, v29
	v_fmac_f32_e32 v14, v89, v29
	v_fmac_f32_e32 v30, v81, v13
	ds_write_b32 v107, v134 offset:12672
	v_fmac_f32_e32 v15, v80, v14
	v_fmac_f32_e32 v31, v80, v30
	v_cvt_pk_bf16_f32 v136, v14, v30
	v_fmac_f32_e32 v15, v89, v30
	v_fmac_f32_e32 v31, v81, v14
	ds_write_b32 v107, v135 offset:13200
	v_fmac_f32_e32 v124, v80, v15
	v_fmac_f32_e32 v172, v80, v31
	v_cvt_pk_bf16_f32 v137, v15, v31
	v_fmac_f32_e32 v124, v89, v31
	v_fmac_f32_e32 v172, v81, v15
	ds_write_b32 v107, v136 offset:13728
	v_fmac_f32_e32 v125, v80, v124
	v_fmac_f32_e32 v173, v80, v172
	v_cvt_pk_bf16_f32 v138, v124, v172
	v_fmac_f32_e32 v125, v89, v172
	v_fmac_f32_e32 v173, v81, v124
	ds_write_b32 v107, v137 offset:14256
	v_fmac_f32_e32 v126, v80, v125
	v_fmac_f32_e32 v174, v80, v173
	v_cvt_pk_bf16_f32 v139, v125, v173
	v_fmac_f32_e32 v126, v89, v173
	v_fmac_f32_e32 v174, v81, v125
	ds_write_b32 v107, v138 offset:14784
	v_fma_f32 v103, v80, v126, v127
	v_fma_f32 v102, v80, v174, v175
	v_cvt_pk_bf16_f32 v134, v126, v174
	v_fmac_f32_e32 v103, v89, v174
	v_fmac_f32_e32 v102, v81, v126
	ds_write_b32 v107, v139 offset:15312
	v_cvt_pk_bf16_f32 v135, v103, v102
	ds_write_b32 v107, v134 offset:15840
	ds_write_b32 v107, v135 offset:16368
	v_mov_b64_e32 v[18:19], s[16:17]
	ds_read_b128 v[194:197], v108 offset:8448
	ds_read_b128 v[198:201], v108 offset:8512
	ds_read_b128 v[202:205], v108 offset:8576
	ds_read_b128 v[206:209], v108 offset:8640
	v_lshlrev_b32_e32 v10, 16, v100
	v_and_b32_e32 v11, 0xffff0000, v100
	v_pk_fma_f32 v[14:15], v[64:65], v[10:11], v[226:227]
	s_nop 0
	v_pk_mul_f32 v[6:7], v[14:15], v[14:15]
	s_nop 0
	v_pk_fma_f32 v[6:7], v[6:7], s[10:11], v[18:19] op_sel_hi:[1,0,0] neg_lo:[1,0,0] neg_hi:[1,0,0]
	s_nop 0
	v_pk_mul_f32 v[6:7], v[14:15], v[6:7]
	s_nop 0
	v_exp_f32_e32 v6, v6
	v_exp_f32_e32 v7, v7
	s_nop 0
	v_pk_add_f32 v[10:11], v[6:7], 1.0 op_sel_hi:[1,0]
	v_lshlrev_b32_e32 v6, 16, v101
	v_and_b32_e32 v7, 0xffff0000, v101
	v_pk_fma_f32 v[20:21], v[66:67], v[6:7], v[228:229]
	v_rcp_f32_e32 v16, v10
	v_pk_mul_f32 v[6:7], v[20:21], v[20:21]
	v_rcp_f32_e32 v17, v11
	v_pk_fma_f32 v[6:7], v[6:7], s[10:11], v[18:19] op_sel_hi:[1,0,0] neg_lo:[1,0,0] neg_hi:[1,0,0]
	s_nop 0
	s_nop 0
	v_pk_mul_f32 v[6:7], v[20:21], v[6:7]
	v_pk_mul_f32 v[24:25], v[14:15], v[16:17]
	v_exp_f32_e32 v12, v6
	v_exp_f32_e32 v13, v7
	s_nop 0
	v_pk_add_f32 v[22:23], v[12:13], 1.0 op_sel_hi:[1,0]
	s_waitcnt lgkmcnt(3)
	v_mfma_f32_16x16x32_bf16 v[6:9], v[48:51], v[194:197], 0
	v_rcp_f32_e32 v22, v22
	v_rcp_f32_e32 v23, v23
	s_waitcnt lgkmcnt(2)
	v_mfma_f32_16x16x32_bf16 v[6:9], v[52:55], v[198:201], v[6:9]
	v_pk_mul_f32 v[20:21], v[20:21], v[22:23]
	v_cvt_pk_bf16_f32 v22, v24, v25
	s_waitcnt lgkmcnt(1)
	v_mfma_f32_16x16x32_bf16 v[6:9], v[56:59], v[202:205], v[6:9]
	s_waitcnt lgkmcnt(0)
	v_mfma_f32_16x16x32_bf16 v[6:9], v[60:63], v[206:209], v[6:9]
	v_lshlrev_b32_e32 v10, 16, v94
	v_and_b32_e32 v11, 0xffff0000, v94
	v_lshlrev_b32_e32 v12, 16, v95
	v_and_b32_e32 v13, 0xffff0000, v95
	s_nop 3
	v_pk_fma_f32 v[6:7], v[64:65], v[10:11], v[6:7]
	v_pk_fma_f32 v[8:9], v[66:67], v[12:13], v[8:9]
	v_pk_mul_f32 v[10:11], v[6:7], v[6:7]
	v_pk_mul_f32 v[12:13], v[8:9], v[8:9]
	v_pk_fma_f32 v[10:11], v[10:11], s[10:11], v[18:19] op_sel_hi:[1,0,0] neg_lo:[1,0,0] neg_hi:[1,0,0]
	v_pk_fma_f32 v[12:13], v[12:13], s[10:11], v[18:19] op_sel_hi:[1,0,0] neg_lo:[1,0,0] neg_hi:[1,0,0]
	v_pk_mul_f32 v[10:11], v[6:7], v[10:11]
	v_pk_mul_f32 v[12:13], v[8:9], v[12:13]
	v_exp_f32_e32 v10, v10
	v_exp_f32_e32 v11, v11
	v_exp_f32_e32 v12, v12
	v_exp_f32_e32 v13, v13
	v_pk_add_f32 v[10:11], v[10:11], 1.0 op_sel_hi:[1,0]
	s_nop 0
	v_rcp_f32_e32 v10, v10
	v_rcp_f32_e32 v11, v11
	v_pk_add_f32 v[12:13], v[12:13], 1.0 op_sel_hi:[1,0]
	v_cvt_pk_bf16_f32 v23, v20, v21
	global_store_dwordx2 v[236:237], v[22:23], off
	v_rcp_f32_e32 v12, v12
	v_rcp_f32_e32 v13, v13
	v_pk_mul_f32 v[6:7], v[6:7], v[10:11]
	s_nop 0
	s_nop 0
	v_cvt_pk_bf16_f32 v6, v6, v7
	v_pk_mul_f32 v[8:9], v[8:9], v[12:13]
	s_nop 0
	v_cvt_pk_bf16_f32 v7, v8, v9
	global_store_dwordx2 v[238:239], v[6:7], off
	v_lshl_add_u64 v[236:237], v[236:237], 0, s[50:51]
	v_lshl_add_u64 v[238:239], v[238:239], 0, s[50:51]
	s_add_i32 s5, s5, 32
	s_add_i32 s6, s6, 1
	s_waitcnt vmcnt(2)
	v_mov_b64_e32 v[100:101], v[190:191]
	v_mov_b64_e32 v[94:95], v[192:193]
	s_cmp_lt_u32 s6, 64
	s_cbranch_scc1 .Ls5p_tile
	s_branch .LBB0_463
